# EpiResid epilogues (D1, D2, OUT): second half-tile's residual rows loaded together with the first half's into registers free during the epilogue (one memory round trip instead of two)
# baseline (speedup 1.0000x reference)
; __device__ __forceinline__ float bflo(unsigned w) { return __uint_as_float(w << 16); }
; __device__ __forceinline__ float bfhi(unsigned w) { return __uint_as_float(w & 0xffff0000u); }
; __device__ __forceinline__ unsigned pk2(float lo, float hi) { return pg8::cvt_pk_bf16(lo, hi); }
;     __device__ __forceinline__ void operator()(const f32x4 (&acc)[2][2][4][2], const Unit& u, int wr, int wc, int fr, int fq) const {
;     ...
;         const int row0 = u.pm * 256 + wr * 64 + fr, col0 = u.pn * 256 + wc * 32 + 4 * fq;
; #pragma unroll
;         for (int hb = 0; hb < 2; ++hb) {
;             u32x2v rin[4][4];
; #pragma unroll
;             for (int gg = 0; gg < 4; ++gg) { const int g = hb * 4 + gg; const size_t offn = (size_t)(row0 + (g >> 2) * 128 + (g & 3) * 16) * D + col0;
; #pragma unroll
;                 for (int k = 0; k < 4; ++k) rin[gg][k] = *(const u32x2v*)(in + offn + (k >> 1) * 128 + (k & 1) * 16); }
; #pragma unroll
;             for (int gg = 0; gg < 4; ++gg) {
;                 const int g = hb * 4 + gg, ai = g >> 2, m = g & 3, row = row0 + ai * 128 + m * 16;
;                 const size_t off = (size_t)row * D + col0;
;                 float ss = 0.f;
; #pragma unroll
;                 for (int k = 0; k < 4; ++k) { const int bj = k >> 1, n = k & 1; const size_t o = off + bj * 128 + n * 16; const f32x4 a = acc[ai][bj][m][n] * scale; const u32x2v w0 = rin[gg][k];
;                     f32x4 r; r[0] = bflo(w0.x) + a[0]; r[1] = bfhi(w0.x) + a[1]; r[2] = bflo(w0.y) + a[2]; r[3] = bfhi(w0.y) + a[3];
;                     u32x2v w; w.x = pk2(r[0], r[1]); w.y = pk2(r[2], r[3]); *(u32x2v*)(out + o) = w; ss += (r[0] * r[0] + r[1] * r[1]) + (r[2] * r[2] + r[3] * r[3]); }
;                 ss += __shfl_xor(ss, 16); ss += __shfl_xor(ss, 32);
;                 if (fq == 0) part[(ai * 128 + wr * 64 + m * 16 + fr) * 4 + wc] = ss;
.LBB0_398:
	s_mov_b64 s[100:101], 0x40000
	s_lshl_b32 s15, s15, 8
	v_lshl_or_b32 v136, s14, 8, v171
	v_readlane_b32 s90, v251, 12
	v_add_u32_e32 v138, s15, v167
	v_ashrrev_i32_e32 v137, 31, v136
	s_mov_b64 s[56:57], s[12:13]
	s_mov_b32 s92, 0.5
	s_mov_b64 s[70:71], s[46:47]
	v_readlane_b32 s91, v251, 13
	v_lshlrev_b64 v[140:141], 1, v[136:137]
	v_ashrrev_i32_e32 v139, 31, v138
	v_lshlrev_b64 v[142:143], 11, v[138:139]
	v_lshl_add_u64 v[136:137], s[56:57], 0, v[140:141]
	v_lshl_add_u64 v[144:145], v[136:137], 0, v[142:143]
	global_load_dwordx2 v[174:175], v[144:145], off
	global_load_dwordx2 v[176:177], v[144:145], off offset:32
	global_load_dwordx2 v[178:179], v[144:145], off offset:256
	global_load_dwordx2 v[180:181], v[144:145], off offset:288
	v_lshl_add_u64 v[202:203], v[144:145], 0, s[100:101]
	global_load_dwordx2 v[204:205], v[202:203], off
	global_load_dwordx2 v[206:207], v[202:203], off offset:32
	global_load_dwordx2 v[210:211], v[202:203], off offset:256
	global_load_dwordx2 v[212:213], v[202:203], off offset:288
	v_or_b32_e32 v144, 16, v138
	v_or_b32_e32 v146, 32, v138
	v_or_b32_e32 v150, 48, v138
	v_ashrrev_i32_e32 v145, 31, v144
	v_ashrrev_i32_e32 v147, 31, v146
	v_ashrrev_i32_e32 v151, 31, v150
	v_lshlrev_b64 v[168:169], 11, v[144:145]
	v_lshlrev_b64 v[148:149], 11, v[146:147]
	v_pk_mul_f32 v[182:183], v[128:129], s[92:93] op_sel_hi:[1,0]
	v_pk_mul_f32 v[188:189], v[122:123], s[92:93] op_sel_hi:[1,0]
	v_pk_mul_f32 v[190:191], v[120:121], s[92:93] op_sel_hi:[1,0]
	v_pk_mul_f32 v[192:193], v[118:119], s[92:93] op_sel_hi:[1,0]
	v_lshl_add_u64 v[118:119], s[70:71], 0, v[140:141]
	v_lshlrev_b64 v[128:129], 11, v[150:151]
	v_lshl_add_u64 v[120:121], v[136:137], 0, v[168:169]
	v_lshl_add_u64 v[122:123], v[136:137], 0, v[148:149]
	v_pk_mul_f32 v[184:185], v[126:127], s[92:93] op_sel_hi:[1,0]
	v_pk_mul_f32 v[186:187], v[124:125], s[92:93] op_sel_hi:[1,0]
	v_lshl_add_u64 v[194:195], v[118:119], 0, v[142:143]
	v_lshl_add_u64 v[196:197], v[136:137], 0, v[128:129]
	global_load_dwordx2 v[156:157], v[120:121], off
	global_load_dwordx2 v[154:155], v[120:121], off offset:32
	global_load_dwordx2 v[152:153], v[120:121], off offset:256
	global_load_dwordx2 v[150:151], v[120:121], off offset:288
	v_lshl_add_u64 v[202:203], v[120:121], 0, s[100:101]
	global_load_dwordx2 v[214:215], v[202:203], off
	global_load_dwordx2 v[216:217], v[202:203], off offset:32
	global_load_dwordx2 v[218:219], v[202:203], off offset:256
	global_load_dwordx2 v[220:221], v[202:203], off offset:288
	global_load_dwordx2 v[146:147], v[122:123], off
	global_load_dwordx2 v[144:145], v[122:123], off offset:32
	global_load_dwordx2 v[142:143], v[122:123], off offset:256
	global_load_dwordx2 v[140:141], v[122:123], off offset:288
	v_lshl_add_u64 v[202:203], v[122:123], 0, s[100:101]
	global_load_dwordx2 v[222:223], v[202:203], off
	global_load_dwordx2 v[224:225], v[202:203], off offset:32
	global_load_dwordx2 v[226:227], v[202:203], off offset:256
	global_load_dwordx2 v[238:239], v[202:203], off offset:288
	global_load_dwordx2 v[126:127], v[196:197], off
	global_load_dwordx2 v[124:125], v[196:197], off offset:32
	s_nop 0
	global_load_dwordx2 v[122:123], v[196:197], off offset:256
	global_load_dwordx2 v[120:121], v[196:197], off offset:288
	v_lshl_add_u64 v[202:203], v[196:197], 0, s[100:101]
	global_load_dwordx2 v[240:241], v[202:203], off
	global_load_dwordx2 v[242:243], v[202:203], off offset:32
	global_load_dwordx2 v[244:245], v[202:203], off offset:256
	global_load_dwordx2 v[246:247], v[202:203], off offset:288
	v_pk_mul_f32 v[114:115], v[114:115], s[92:93] op_sel_hi:[1,0]
	v_pk_mul_f32 v[116:117], v[116:117], s[92:93] op_sel_hi:[1,0]
	s_waitcnt vmcnt(0) lgkmcnt(0)
	v_lshlrev_b32_e32 v196, 16, v174
	v_and_b32_e32 v174, 0xffff0000, v174
	v_lshlrev_b32_e32 v197, 16, v175
	v_and_b32_e32 v175, 0xffff0000, v175
	v_lshlrev_b32_e32 v198, 16, v176
	v_and_b32_e32 v176, 0xffff0000, v176
	v_lshlrev_b32_e32 v199, 16, v177
	v_and_b32_e32 v177, 0xffff0000, v177
	v_lshlrev_b32_e32 v201, 16, v179
	v_and_b32_e32 v179, 0xffff0000, v179
	v_add_f32_e32 v185, v185, v174
	v_add_f32_e32 v183, v183, v175
	v_add_f32_e32 v176, v189, v176
	v_add_f32_e32 v177, v187, v177
	v_add_f32_e32 v184, v184, v196
	v_add_f32_e32 v182, v182, v197
	v_add_f32_e32 v188, v188, v198
	v_add_f32_e32 v186, v186, v199
	v_add_f32_e32 v189, v190, v201
	v_add_f32_e32 v179, v191, v179
	v_cvt_pk_bf16_f32 v174, v184, v185
	v_cvt_pk_bf16_f32 v175, v182, v183
	v_mul_f32_e32 v185, v185, v185
	v_mul_f32_e32 v183, v183, v183
	v_mul_f32_e32 v190, v176, v176
	v_mul_f32_e32 v191, v177, v177
	v_lshlrev_b32_e32 v200, 16, v178
	v_and_b32_e32 v178, 0xffff0000, v178
	v_fmac_f32_e32 v185, v184, v184
	v_fmac_f32_e32 v183, v182, v182
	v_fmac_f32_e32 v190, v188, v188
	v_fmac_f32_e32 v191, v186, v186
	v_add_f32_e32 v178, v193, v178
	global_store_dwordx2 v[194:195], v[174:175], off
	v_cvt_pk_bf16_f32 v174, v188, v176
	v_add_f32_e32 v175, v185, v183
	v_add_f32_e32 v176, v190, v191
	v_add_f32_e32 v187, v192, v200
	v_mul_f32_e32 v192, v178, v178
	v_add_f32_e32 v175, v175, v176
	v_mul_f32_e32 v176, v179, v179
	v_fmac_f32_e32 v192, v187, v187
	v_fmac_f32_e32 v176, v189, v189
	v_add_f32_e32 v176, v192, v176
	v_add_f32_e32 v175, v175, v176
	v_lshlrev_b32_e32 v176, 16, v180
	v_add_f32_e32 v176, v114, v176
	v_and_b32_e32 v114, 0xffff0000, v180
	v_add_f32_e32 v180, v115, v114
	v_lshlrev_b32_e32 v114, 16, v181
	v_add_f32_e32 v182, v116, v114
	v_and_b32_e32 v114, 0xffff0000, v181
	v_add_f32_e32 v181, v117, v114
	v_mul_f32_e32 v114, v180, v180
	v_mul_f32_e32 v115, v181, v181
	v_fmac_f32_e32 v114, v176, v176
	v_fmac_f32_e32 v115, v182, v182
	v_add_f32_e32 v114, v114, v115
	v_and_b32_e32 v116, 64, v209
	v_add_f32_e32 v115, v175, v114
	v_xor_b32_e32 v114, 16, v209
	v_add_u32_e32 v117, 64, v116
	v_cmp_lt_i32_e32 vcc, v114, v117
	v_cvt_pk_bf16_f32 v175, v186, v177
	global_store_dwordx2 v[194:195], v[174:175], off offset:32
	v_cvt_pk_bf16_f32 v174, v187, v178
	v_cvt_pk_bf16_f32 v175, v189, v179
	global_store_dwordx2 v[194:195], v[174:175], off offset:256
	v_cndmask_b32_e32 v114, v209, v114, vcc
	v_lshlrev_b32_e32 v114, 2, v114
	ds_bpermute_b32 v116, v114, v115
	v_cvt_pk_bf16_f32 v174, v176, v180
	v_cvt_pk_bf16_f32 v175, v182, v181
	global_store_dwordx2 v[194:195], v[174:175], off offset:288
	s_waitcnt lgkmcnt(0)
	v_add_f32_e32 v116, v115, v116
	v_xor_b32_e32 v115, 32, v209
	v_cmp_lt_i32_e32 vcc, v115, v117
	s_nop 1
	v_cndmask_b32_e32 v115, v209, v115, vcc
	v_lshlrev_b32_e32 v115, 2, v115
	ds_bpermute_b32 v117, v115, v116
	s_and_saveexec_b64 s[70:71], s[40:41]
	s_cbranch_execz .LBB0_400
	s_waitcnt lgkmcnt(0)
	v_add_f32_e32 v116, v116, v117
	ds_write_b32 v172, v116

; __device__ __forceinline__ float bflo(unsigned w) { return __uint_as_float(w << 16); }
; __device__ __forceinline__ float bfhi(unsigned w) { return __uint_as_float(w & 0xffff0000u); }
; __device__ __forceinline__ unsigned pk2(float lo, float hi) { return pg8::cvt_pk_bf16(lo, hi); }
;     __device__ __forceinline__ void operator()(const f32x4 (&acc)[2][2][4][2], const Unit& u, int wr, int wc, int fr, int fq) const {
;     ...
;             for (int gg = 0; gg < 4; ++gg) { const int g = hb * 4 + gg; const size_t offn = (size_t)(row0 + (g >> 2) * 128 + (g & 3) * 16) * D + col0;
; #pragma unroll
;                 for (int k = 0; k < 4; ++k) rin[gg][k] = *(const u32x2v*)(in + offn + (k >> 1) * 128 + (k & 1) * 16); }
; #pragma unroll
;             for (int gg = 0; gg < 4; ++gg) {
;                 const int g = hb * 4 + gg, ai = g >> 2, m = g & 3, row = row0 + ai * 128 + m * 16;
;                 const size_t off = (size_t)row * D + col0;
;                 float ss = 0.f;
; #pragma unroll
;                 for (int k = 0; k < 4; ++k) { const int bj = k >> 1, n = k & 1; const size_t o = off + bj * 128 + n * 16; const f32x4 a = acc[ai][bj][m][n] * scale; const u32x2v w0 = rin[gg][k];
;                     f32x4 r; r[0] = bflo(w0.x) + a[0]; r[1] = bfhi(w0.x) + a[1]; r[2] = bflo(w0.y) + a[2]; r[3] = bfhi(w0.y) + a[3];
;                     u32x2v w; w.x = pk2(r[0], r[1]); w.y = pk2(r[2], r[3]); *(u32x2v*)(out + o) = w; ss += (r[0] * r[0] + r[1] * r[1]) + (r[2] * r[2] + r[3] * r[3]); }
;                 ss += __shfl_xor(ss, 16); ss += __shfl_xor(ss, 32);
;                 if (fq == 0) part[(ai * 128 + wr * 64 + m * 16 + fr) * 4 + wc] = ss;
.LBB0_406:
	s_or_b64 exec, exec, vcc
	s_waitcnt lgkmcnt(0)
	v_lshlrev_b64 v[66:67], 11, v[138:139]
	v_lshl_add_u64 v[98:99], v[66:67], 0, s[88:89]
	v_lshl_add_u64 v[68:69], v[136:137], 0, v[98:99]
	s_mov_b64 s[56:57], 0x48000
	v_lshl_add_u64 v[94:95], v[66:67], 0, s[56:57]
	s_mov_b64 s[56:57], 0x50000
	v_lshl_add_u64 v[84:85], v[66:67], 0, s[56:57]
	s_mov_b64 s[56:57], 0x58000
	v_lshl_add_u64 v[68:69], v[136:137], 0, v[94:95]
	v_lshl_add_u64 v[70:71], v[66:67], 0, s[56:57]
	v_lshl_add_u64 v[68:69], v[136:137], 0, v[84:85]
	v_lshl_add_u64 v[66:67], v[136:137], 0, v[70:71]
	s_nop 0
	s_nop 0
	v_pk_mul_f32 v[62:63], v[62:63], s[92:93]
	v_pk_mul_f32 v[64:65], v[64:65], s[70:71]
	v_lshl_add_u64 v[98:99], v[118:119], 0, v[98:99]
	v_pk_mul_f32 v[58:59], v[58:59], s[92:93]
	v_pk_mul_f32 v[60:61], v[60:61], s[70:71]
	v_pk_mul_f32 v[54:55], v[54:55], s[92:93]
	v_pk_mul_f32 v[56:57], v[56:57], s[70:71]
	v_pk_mul_f32 v[50:51], v[50:51], s[92:93]
	v_pk_mul_f32 v[52:53], v[52:53], s[70:71]
	s_waitcnt vmcnt(0) lgkmcnt(0)
	v_mov_b32_e32 v102, v204
	v_mov_b32_e32 v103, v205
	v_mov_b32_e32 v104, v206
	v_mov_b32_e32 v105, v207
	v_mov_b32_e32 v100, v210
	v_mov_b32_e32 v101, v211
	v_mov_b32_e32 v96, v212
	v_mov_b32_e32 v97, v213
	v_mov_b32_e32 v92, v214
	v_mov_b32_e32 v93, v215
	v_mov_b32_e32 v90, v216
	v_mov_b32_e32 v91, v217
	v_mov_b32_e32 v88, v218
	v_mov_b32_e32 v89, v219
	v_mov_b32_e32 v86, v220
	v_mov_b32_e32 v87, v221
	v_mov_b32_e32 v82, v222
	v_mov_b32_e32 v83, v223
	v_mov_b32_e32 v80, v224
	v_mov_b32_e32 v81, v225
	v_mov_b32_e32 v78, v226
	v_mov_b32_e32 v79, v227
	v_mov_b32_e32 v74, v238
	v_mov_b32_e32 v75, v239
	v_mov_b32_e32 v76, v240
	v_mov_b32_e32 v77, v241
	v_mov_b32_e32 v72, v242
	v_mov_b32_e32 v73, v243
	v_mov_b32_e32 v68, v244
	v_mov_b32_e32 v69, v245
	v_mov_b32_e32 v66, v246
	v_mov_b32_e32 v67, v247
	v_lshlrev_b32_e32 v106, 16, v102
	v_add_f32_e32 v106, v62, v106
	v_and_b32_e32 v62, 0xffff0000, v102
	v_add_f32_e32 v102, v63, v62
	v_lshlrev_b32_e32 v62, 16, v103
	v_add_f32_e32 v64, v64, v62
	v_and_b32_e32 v62, 0xffff0000, v103
	v_add_f32_e32 v65, v65, v62
	v_cvt_pk_bf16_f32 v62, v106, v102
	v_cvt_pk_bf16_f32 v63, v64, v65
	global_store_dwordx2 v[98:99], v[62:63], off
	v_mul_f32_e32 v62, v102, v102
	v_mul_f32_e32 v63, v65, v65
	v_fmac_f32_e32 v62, v106, v106
	v_fmac_f32_e32 v63, v64, v64
	v_add_f32_e32 v62, v62, v63
	v_lshlrev_b32_e32 v63, 16, v104
	v_add_f32_e32 v63, v58, v63
	v_and_b32_e32 v58, 0xffff0000, v104
	v_add_f32_e32 v64, v59, v58
	v_lshlrev_b32_e32 v58, 16, v105
	v_add_f32_e32 v60, v60, v58
	v_and_b32_e32 v58, 0xffff0000, v105
	v_add_f32_e32 v61, v61, v58
	v_cvt_pk_bf16_f32 v58, v63, v64
	v_cvt_pk_bf16_f32 v59, v60, v61
	global_store_dwordx2 v[98:99], v[58:59], off offset:32
	v_mul_f32_e32 v58, v64, v64
	v_mul_f32_e32 v59, v61, v61
	v_fmac_f32_e32 v58, v63, v63
	v_fmac_f32_e32 v59, v60, v60
	v_add_f32_e32 v58, v58, v59
	v_lshlrev_b32_e32 v59, 16, v100
	v_add_f32_e32 v59, v54, v59
	v_and_b32_e32 v54, 0xffff0000, v100
	v_add_f32_e32 v60, v55, v54
	v_lshlrev_b32_e32 v54, 16, v101
	v_add_f32_e32 v56, v56, v54
	v_and_b32_e32 v54, 0xffff0000, v101
	v_add_f32_e32 v57, v57, v54
	v_cvt_pk_bf16_f32 v54, v59, v60
	v_cvt_pk_bf16_f32 v55, v56, v57
	global_store_dwordx2 v[98:99], v[54:55], off offset:256
	v_mul_f32_e32 v54, v60, v60
	v_mul_f32_e32 v55, v57, v57
	v_fmac_f32_e32 v54, v59, v59
	v_fmac_f32_e32 v55, v56, v56
	v_add_f32_e32 v54, v54, v55
	v_lshlrev_b32_e32 v55, 16, v96
	v_add_f32_e32 v55, v50, v55
	v_and_b32_e32 v50, 0xffff0000, v96
	v_add_f32_e32 v56, v51, v50
	v_lshlrev_b32_e32 v50, 16, v97
	v_add_f32_e32 v52, v52, v50
	v_and_b32_e32 v50, 0xffff0000, v97
	v_add_f32_e32 v53, v53, v50
	v_cvt_pk_bf16_f32 v50, v55, v56
	v_cvt_pk_bf16_f32 v51, v52, v53
	global_store_dwordx2 v[98:99], v[50:51], off offset:288
	v_mul_f32_e32 v50, v56, v56
	v_mul_f32_e32 v51, v53, v53
	v_add_f32_e32 v58, v62, v58
	v_fmac_f32_e32 v50, v55, v55
	v_fmac_f32_e32 v51, v52, v52
	v_add_f32_e32 v54, v58, v54
	v_add_f32_e32 v50, v50, v51
	v_add_f32_e32 v50, v54, v50
	ds_bpermute_b32 v51, v114, v50
	s_waitcnt lgkmcnt(0)
	v_add_f32_e32 v50, v50, v51
	ds_bpermute_b32 v51, v115, v50
	s_and_saveexec_b64 s[70:71], s[40:41]
	s_cbranch_execz .LBB0_408
	s_waitcnt lgkmcnt(0)
	v_add_f32_e32 v50, v50, v51
	ds_write_b32 v172, v50 offset:2048

; __device__ __forceinline__ float bflo(unsigned w) { return __uint_as_float(w << 16); }
; __device__ __forceinline__ float bfhi(unsigned w) { return __uint_as_float(w & 0xffff0000u); }
; __device__ __forceinline__ unsigned pk2(float lo, float hi) { return pg8::cvt_pk_bf16(lo, hi); }
;     __device__ __forceinline__ void operator()(const f32x4 (&acc)[2][2][4][2], const Unit& u, int wr, int wc, int fr, int fq) const {
;     ...
;         const int row0 = u.pm * 256 + wr * 64 + fr, col0 = u.pn * 256 + wc * 32 + 4 * fq;
; #pragma unroll
;         for (int hb = 0; hb < 2; ++hb) {
;             u32x2v rin[4][4];
; #pragma unroll
;             for (int gg = 0; gg < 4; ++gg) { const int g = hb * 4 + gg; const size_t offn = (size_t)(row0 + (g >> 2) * 128 + (g & 3) * 16) * D + col0;
; #pragma unroll
;                 for (int k = 0; k < 4; ++k) rin[gg][k] = *(const u32x2v*)(in + offn + (k >> 1) * 128 + (k & 1) * 16); }
; #pragma unroll
;             for (int gg = 0; gg < 4; ++gg) {
;                 const int g = hb * 4 + gg, ai = g >> 2, m = g & 3, row = row0 + ai * 128 + m * 16;
;                 const size_t off = (size_t)row * D + col0;
;                 float ss = 0.f;
; #pragma unroll
;                 for (int k = 0; k < 4; ++k) { const int bj = k >> 1, n = k & 1; const size_t o = off + bj * 128 + n * 16; const f32x4 a = acc[ai][bj][m][n] * scale; const u32x2v w0 = rin[gg][k];
;                     f32x4 r; r[0] = bflo(w0.x) + a[0]; r[1] = bfhi(w0.x) + a[1]; r[2] = bflo(w0.y) + a[2]; r[3] = bfhi(w0.y) + a[3];
;                     u32x2v w; w.x = pk2(r[0], r[1]); w.y = pk2(r[2], r[3]); *(u32x2v*)(out + o) = w; ss += (r[0] * r[0] + r[1] * r[1]) + (r[2] * r[2] + r[3] * r[3]); }
;                 ss += __shfl_xor(ss, 16); ss += __shfl_xor(ss, 32);
;                 if (fq == 0) part[(ai * 128 + wr * 64 + m * 16 + fr) * 4 + wc] = ss;
.LBB0_1103:
	s_mov_b64 s[100:101], 0x40000
	s_lshl_b32 s13, s13, 8
	v_lshl_or_b32 v136, s12, 8, v170
	v_readlane_b32 s80, v250, 28
	v_add_u32_e32 v138, s13, v168
	v_ashrrev_i32_e32 v137, 31, v136
	v_readlane_b32 s81, v250, 29
	s_mov_b64 s[56:57], s[46:47]
	s_mov_b64 s[70:71], s[46:47]
	s_mov_b32 s90, 1.0
	v_lshlrev_b64 v[140:141], 1, v[136:137]
	v_ashrrev_i32_e32 v139, 31, v138
	v_lshlrev_b64 v[142:143], 11, v[138:139]
	v_lshl_add_u64 v[136:137], s[56:57], 0, v[140:141]
	v_lshl_add_u64 v[144:145], v[136:137], 0, v[142:143]
	global_load_dwordx2 v[174:175], v[144:145], off
	global_load_dwordx2 v[176:177], v[144:145], off offset:32
	global_load_dwordx2 v[178:179], v[144:145], off offset:256
	global_load_dwordx2 v[180:181], v[144:145], off offset:288
	v_lshl_add_u64 v[202:203], v[144:145], 0, s[100:101]
	global_load_dwordx2 v[204:205], v[202:203], off
	global_load_dwordx2 v[206:207], v[202:203], off offset:32
	global_load_dwordx2 v[210:211], v[202:203], off offset:256
	global_load_dwordx2 v[212:213], v[202:203], off offset:288
	v_or_b32_e32 v144, 16, v138
	v_or_b32_e32 v146, 32, v138
	v_or_b32_e32 v150, 48, v138
	v_ashrrev_i32_e32 v145, 31, v144
	v_ashrrev_i32_e32 v147, 31, v146
	v_ashrrev_i32_e32 v151, 31, v150
	v_lshlrev_b64 v[166:167], 11, v[144:145]
	v_lshlrev_b64 v[148:149], 11, v[146:147]
	v_pk_mul_f32 v[182:183], v[128:129], s[90:91] op_sel_hi:[1,0]
	v_pk_mul_f32 v[188:189], v[122:123], s[90:91] op_sel_hi:[1,0]
	v_pk_mul_f32 v[190:191], v[120:121], s[90:91] op_sel_hi:[1,0]
	v_pk_mul_f32 v[192:193], v[118:119], s[90:91] op_sel_hi:[1,0]
	v_lshl_add_u64 v[118:119], s[70:71], 0, v[140:141]
	v_lshlrev_b64 v[128:129], 11, v[150:151]
	v_lshl_add_u64 v[120:121], v[136:137], 0, v[166:167]
	v_lshl_add_u64 v[122:123], v[136:137], 0, v[148:149]
	v_pk_mul_f32 v[184:185], v[126:127], s[90:91] op_sel_hi:[1,0]
	v_pk_mul_f32 v[186:187], v[124:125], s[90:91] op_sel_hi:[1,0]
	v_lshl_add_u64 v[194:195], v[118:119], 0, v[142:143]
	v_lshl_add_u64 v[196:197], v[136:137], 0, v[128:129]
	global_load_dwordx2 v[156:157], v[120:121], off
	global_load_dwordx2 v[154:155], v[120:121], off offset:32
	global_load_dwordx2 v[152:153], v[120:121], off offset:256
	global_load_dwordx2 v[150:151], v[120:121], off offset:288
	v_lshl_add_u64 v[202:203], v[120:121], 0, s[100:101]
	global_load_dwordx2 v[214:215], v[202:203], off
	global_load_dwordx2 v[216:217], v[202:203], off offset:32
	global_load_dwordx2 v[218:219], v[202:203], off offset:256
	global_load_dwordx2 v[220:221], v[202:203], off offset:288
	global_load_dwordx2 v[146:147], v[122:123], off
	global_load_dwordx2 v[144:145], v[122:123], off offset:32
	global_load_dwordx2 v[142:143], v[122:123], off offset:256
	global_load_dwordx2 v[140:141], v[122:123], off offset:288
	v_lshl_add_u64 v[202:203], v[122:123], 0, s[100:101]
	global_load_dwordx2 v[222:223], v[202:203], off
	global_load_dwordx2 v[224:225], v[202:203], off offset:32
	global_load_dwordx2 v[226:227], v[202:203], off offset:256
	global_load_dwordx2 v[238:239], v[202:203], off offset:288
	global_load_dwordx2 v[126:127], v[196:197], off
	global_load_dwordx2 v[124:125], v[196:197], off offset:32
	s_nop 0
	global_load_dwordx2 v[122:123], v[196:197], off offset:256
	global_load_dwordx2 v[120:121], v[196:197], off offset:288
	v_lshl_add_u64 v[202:203], v[196:197], 0, s[100:101]
	global_load_dwordx2 v[240:241], v[202:203], off
	global_load_dwordx2 v[242:243], v[202:203], off offset:32
	global_load_dwordx2 v[244:245], v[202:203], off offset:256
	global_load_dwordx2 v[246:247], v[202:203], off offset:288
	v_pk_mul_f32 v[114:115], v[114:115], s[90:91] op_sel_hi:[1,0]
	v_pk_mul_f32 v[116:117], v[116:117], s[90:91] op_sel_hi:[1,0]
	s_waitcnt vmcnt(0) lgkmcnt(0)
	v_lshlrev_b32_e32 v173, 16, v174
	v_and_b32_e32 v174, 0xffff0000, v174
	v_lshlrev_b32_e32 v196, 16, v175
	v_and_b32_e32 v175, 0xffff0000, v175
	v_lshlrev_b32_e32 v197, 16, v176
	v_and_b32_e32 v176, 0xffff0000, v176
	v_lshlrev_b32_e32 v198, 16, v177
	v_and_b32_e32 v177, 0xffff0000, v177
	v_lshlrev_b32_e32 v200, 16, v179
	v_add_f32_e32 v173, v184, v173
	v_add_f32_e32 v184, v185, v174
	v_add_f32_e32 v183, v183, v175
	v_add_f32_e32 v176, v189, v176
	v_add_f32_e32 v177, v187, v177
	v_add_f32_e32 v182, v182, v196
	v_add_f32_e32 v185, v188, v197
	v_add_f32_e32 v186, v186, v198
	v_add_f32_e32 v188, v190, v200
	v_cvt_pk_bf16_f32 v174, v173, v184
	v_cvt_pk_bf16_f32 v175, v182, v183
	v_mul_f32_e32 v184, v184, v184
	v_mul_f32_e32 v183, v183, v183
	v_mul_f32_e32 v189, v176, v176
	v_mul_f32_e32 v190, v177, v177
	v_lshlrev_b32_e32 v199, 16, v178
	v_and_b32_e32 v178, 0xffff0000, v178
	v_and_b32_e32 v179, 0xffff0000, v179
	v_fmac_f32_e32 v184, v173, v173
	v_fmac_f32_e32 v183, v182, v182
	v_fmac_f32_e32 v189, v185, v185
	v_fmac_f32_e32 v190, v186, v186
	v_add_f32_e32 v178, v193, v178
	v_add_f32_e32 v179, v191, v179
	global_store_dwordx2 v[194:195], v[174:175], off
	v_add_f32_e32 v173, v184, v183
	v_add_f32_e32 v175, v189, v190
	v_add_f32_e32 v187, v192, v199
	v_mul_f32_e32 v191, v178, v178
	v_add_f32_e32 v173, v173, v175
	v_mul_f32_e32 v175, v179, v179
	v_fmac_f32_e32 v191, v187, v187
	v_fmac_f32_e32 v175, v188, v188
	v_add_f32_e32 v175, v191, v175
	v_add_f32_e32 v173, v173, v175
	v_lshlrev_b32_e32 v175, 16, v180
	v_cvt_pk_bf16_f32 v174, v185, v176
	v_add_f32_e32 v176, v114, v175
	v_and_b32_e32 v114, 0xffff0000, v180
	v_add_f32_e32 v180, v115, v114
	v_lshlrev_b32_e32 v114, 16, v181
	v_add_f32_e32 v182, v116, v114
	v_and_b32_e32 v114, 0xffff0000, v181
	v_add_f32_e32 v181, v117, v114
	v_mul_f32_e32 v114, v180, v180
	v_mul_f32_e32 v115, v181, v181
	v_fmac_f32_e32 v114, v176, v176
	v_fmac_f32_e32 v115, v182, v182
	v_add_f32_e32 v114, v114, v115
	v_and_b32_e32 v116, 64, v209
	v_add_f32_e32 v115, v173, v114
	v_xor_b32_e32 v114, 16, v209
	v_add_u32_e32 v117, 64, v116
	v_cmp_lt_i32_e32 vcc, v114, v117
	v_cvt_pk_bf16_f32 v175, v186, v177
	global_store_dwordx2 v[194:195], v[174:175], off offset:32
	v_cvt_pk_bf16_f32 v174, v187, v178
	v_cvt_pk_bf16_f32 v175, v188, v179
	global_store_dwordx2 v[194:195], v[174:175], off offset:256
	v_cndmask_b32_e32 v114, v209, v114, vcc
	v_lshlrev_b32_e32 v114, 2, v114
	ds_bpermute_b32 v116, v114, v115
	v_cvt_pk_bf16_f32 v174, v176, v180
	v_cvt_pk_bf16_f32 v175, v182, v181
	global_store_dwordx2 v[194:195], v[174:175], off offset:288
	s_waitcnt lgkmcnt(0)
	v_add_f32_e32 v116, v115, v116
	v_xor_b32_e32 v115, 32, v209
	v_cmp_lt_i32_e32 vcc, v115, v117
	s_nop 1
	v_cndmask_b32_e32 v115, v209, v115, vcc
	v_lshlrev_b32_e32 v115, 2, v115
	ds_bpermute_b32 v117, v115, v116
	s_and_saveexec_b64 s[70:71], s[40:41]
	s_cbranch_execz .LBB0_1105
	s_waitcnt lgkmcnt(0)
	v_add_f32_e32 v116, v116, v117
	ds_write_b32 v171, v116

; __device__ __forceinline__ float bflo(unsigned w) { return __uint_as_float(w << 16); }
; __device__ __forceinline__ float bfhi(unsigned w) { return __uint_as_float(w & 0xffff0000u); }
; __device__ __forceinline__ unsigned pk2(float lo, float hi) { return pg8::cvt_pk_bf16(lo, hi); }
;     __device__ __forceinline__ void operator()(const f32x4 (&acc)[2][2][4][2], const Unit& u, int wr, int wc, int fr, int fq) const {
;     ...
;             for (int gg = 0; gg < 4; ++gg) { const int g = hb * 4 + gg; const size_t offn = (size_t)(row0 + (g >> 2) * 128 + (g & 3) * 16) * D + col0;
; #pragma unroll
;                 for (int k = 0; k < 4; ++k) rin[gg][k] = *(const u32x2v*)(in + offn + (k >> 1) * 128 + (k & 1) * 16); }
; #pragma unroll
;             for (int gg = 0; gg < 4; ++gg) {
;                 const int g = hb * 4 + gg, ai = g >> 2, m = g & 3, row = row0 + ai * 128 + m * 16;
;                 const size_t off = (size_t)row * D + col0;
;                 float ss = 0.f;
; #pragma unroll
;                 for (int k = 0; k < 4; ++k) { const int bj = k >> 1, n = k & 1; const size_t o = off + bj * 128 + n * 16; const f32x4 a = acc[ai][bj][m][n] * scale; const u32x2v w0 = rin[gg][k];
;                     f32x4 r; r[0] = bflo(w0.x) + a[0]; r[1] = bfhi(w0.x) + a[1]; r[2] = bflo(w0.y) + a[2]; r[3] = bfhi(w0.y) + a[3];
;                     u32x2v w; w.x = pk2(r[0], r[1]); w.y = pk2(r[2], r[3]); *(u32x2v*)(out + o) = w; ss += (r[0] * r[0] + r[1] * r[1]) + (r[2] * r[2] + r[3] * r[3]); }
;                 ss += __shfl_xor(ss, 16); ss += __shfl_xor(ss, 32);
;                 if (fq == 0) part[(ai * 128 + wr * 64 + m * 16 + fr) * 4 + wc] = ss;
.LBB0_1111:
	s_or_b64 exec, exec, s[92:93]
	s_waitcnt lgkmcnt(0)
	v_lshlrev_b64 v[66:67], 11, v[138:139]
	v_lshl_add_u64 v[98:99], v[66:67], 0, s[88:89]
	v_lshl_add_u64 v[68:69], v[136:137], 0, v[98:99]
	s_mov_b64 s[56:57], 0x48000
	v_lshl_add_u64 v[94:95], v[66:67], 0, s[56:57]
	s_mov_b64 s[56:57], 0x50000
	v_lshl_add_u64 v[84:85], v[66:67], 0, s[56:57]
	s_mov_b64 s[56:57], 0x58000
	v_lshl_add_u64 v[68:69], v[136:137], 0, v[94:95]
	v_lshl_add_u64 v[70:71], v[66:67], 0, s[56:57]
	v_lshl_add_u64 v[68:69], v[136:137], 0, v[84:85]
	v_lshl_add_u64 v[66:67], v[136:137], 0, v[70:71]
	s_nop 0
	s_nop 0
	v_pk_mul_f32 v[62:63], v[62:63], s[90:91]
	v_pk_mul_f32 v[64:65], v[64:65], s[70:71]
	v_lshl_add_u64 v[98:99], v[118:119], 0, v[98:99]
	v_pk_mul_f32 v[58:59], v[58:59], s[90:91]
	v_pk_mul_f32 v[60:61], v[60:61], s[70:71]
	v_pk_mul_f32 v[54:55], v[54:55], s[90:91]
	v_pk_mul_f32 v[56:57], v[56:57], s[70:71]
	v_pk_mul_f32 v[50:51], v[50:51], s[90:91]
	v_pk_mul_f32 v[52:53], v[52:53], s[70:71]
	s_waitcnt vmcnt(0) lgkmcnt(0)
	v_mov_b32_e32 v102, v204
	v_mov_b32_e32 v103, v205
	v_mov_b32_e32 v104, v206
	v_mov_b32_e32 v105, v207
	v_mov_b32_e32 v100, v210
	v_mov_b32_e32 v101, v211
	v_mov_b32_e32 v96, v212
	v_mov_b32_e32 v97, v213
	v_mov_b32_e32 v92, v214
	v_mov_b32_e32 v93, v215
	v_mov_b32_e32 v90, v216
	v_mov_b32_e32 v91, v217
	v_mov_b32_e32 v88, v218
	v_mov_b32_e32 v89, v219
	v_mov_b32_e32 v86, v220
	v_mov_b32_e32 v87, v221
	v_mov_b32_e32 v82, v222
	v_mov_b32_e32 v83, v223
	v_mov_b32_e32 v80, v224
	v_mov_b32_e32 v81, v225
	v_mov_b32_e32 v78, v226
	v_mov_b32_e32 v79, v227
	v_mov_b32_e32 v74, v238
	v_mov_b32_e32 v75, v239
	v_mov_b32_e32 v76, v240
	v_mov_b32_e32 v77, v241
	v_mov_b32_e32 v72, v242
	v_mov_b32_e32 v73, v243
	v_mov_b32_e32 v68, v244
	v_mov_b32_e32 v69, v245
	v_mov_b32_e32 v66, v246
	v_mov_b32_e32 v67, v247
	v_lshlrev_b32_e32 v106, 16, v102
	v_add_f32_e32 v106, v62, v106
	v_and_b32_e32 v62, 0xffff0000, v102
	v_add_f32_e32 v102, v63, v62
	v_lshlrev_b32_e32 v62, 16, v103
	v_add_f32_e32 v64, v64, v62
	v_and_b32_e32 v62, 0xffff0000, v103
	v_add_f32_e32 v65, v65, v62
	v_cvt_pk_bf16_f32 v62, v106, v102
	v_cvt_pk_bf16_f32 v63, v64, v65
	global_store_dwordx2 v[98:99], v[62:63], off
	v_mul_f32_e32 v62, v102, v102
	v_mul_f32_e32 v63, v65, v65
	v_fmac_f32_e32 v62, v106, v106
	v_fmac_f32_e32 v63, v64, v64
	v_add_f32_e32 v62, v62, v63
	v_lshlrev_b32_e32 v63, 16, v104
	v_add_f32_e32 v63, v58, v63
	v_and_b32_e32 v58, 0xffff0000, v104
	v_add_f32_e32 v64, v59, v58
	v_lshlrev_b32_e32 v58, 16, v105
	v_add_f32_e32 v60, v60, v58
	v_and_b32_e32 v58, 0xffff0000, v105
	v_add_f32_e32 v61, v61, v58
	v_cvt_pk_bf16_f32 v58, v63, v64
	v_cvt_pk_bf16_f32 v59, v60, v61
	global_store_dwordx2 v[98:99], v[58:59], off offset:32
	v_mul_f32_e32 v58, v64, v64
	v_mul_f32_e32 v59, v61, v61
	v_fmac_f32_e32 v58, v63, v63
	v_fmac_f32_e32 v59, v60, v60
	v_add_f32_e32 v58, v58, v59
	v_lshlrev_b32_e32 v59, 16, v100
	v_add_f32_e32 v59, v54, v59
	v_and_b32_e32 v54, 0xffff0000, v100
	v_add_f32_e32 v60, v55, v54
	v_lshlrev_b32_e32 v54, 16, v101
	v_add_f32_e32 v56, v56, v54
	v_and_b32_e32 v54, 0xffff0000, v101
	v_add_f32_e32 v57, v57, v54
	v_cvt_pk_bf16_f32 v54, v59, v60
	v_cvt_pk_bf16_f32 v55, v56, v57
	global_store_dwordx2 v[98:99], v[54:55], off offset:256
	v_mul_f32_e32 v54, v60, v60
	v_mul_f32_e32 v55, v57, v57
	v_fmac_f32_e32 v54, v59, v59
	v_fmac_f32_e32 v55, v56, v56
	v_add_f32_e32 v54, v54, v55
	v_lshlrev_b32_e32 v55, 16, v96
	v_add_f32_e32 v55, v50, v55
	v_and_b32_e32 v50, 0xffff0000, v96
	v_add_f32_e32 v56, v51, v50
	v_lshlrev_b32_e32 v50, 16, v97
	v_add_f32_e32 v52, v52, v50
	v_and_b32_e32 v50, 0xffff0000, v97
	v_add_f32_e32 v53, v53, v50
	v_cvt_pk_bf16_f32 v50, v55, v56
	v_cvt_pk_bf16_f32 v51, v52, v53
	global_store_dwordx2 v[98:99], v[50:51], off offset:288
	v_mul_f32_e32 v50, v56, v56
	v_mul_f32_e32 v51, v53, v53
	v_add_f32_e32 v58, v62, v58
	v_fmac_f32_e32 v50, v55, v55
	v_fmac_f32_e32 v51, v52, v52
	v_add_f32_e32 v54, v58, v54
	v_add_f32_e32 v50, v50, v51
	v_add_f32_e32 v50, v54, v50
	ds_bpermute_b32 v51, v114, v50
	s_waitcnt lgkmcnt(0)
	v_add_f32_e32 v50, v50, v51
	ds_bpermute_b32 v51, v115, v50
	s_and_saveexec_b64 s[70:71], s[40:41]
	s_cbranch_execz .LBB0_1113
	s_waitcnt lgkmcnt(0)
	v_add_f32_e32 v50, v50, v51
	ds_write_b32 v171, v50 offset:2048

; __device__ __forceinline__ float bflo(unsigned w) { return __uint_as_float(w << 16); }
; __device__ __forceinline__ float bfhi(unsigned w) { return __uint_as_float(w & 0xffff0000u); }
; __device__ __forceinline__ unsigned pk2(float lo, float hi) { return pg8::cvt_pk_bf16(lo, hi); }
;     __device__ __forceinline__ void operator()(const f32x4 (&acc)[2][2][4][2], const Unit& u, int wr, int wc, int fr, int fq) const {
;     ...
;         const int row0 = u.pm * 256 + wr * 64 + fr, col0 = u.pn * 256 + wc * 32 + 4 * fq;
; #pragma unroll
;         for (int hb = 0; hb < 2; ++hb) {
;             u32x2v rin[4][4];
; #pragma unroll
;             for (int gg = 0; gg < 4; ++gg) { const int g = hb * 4 + gg; const size_t offn = (size_t)(row0 + (g >> 2) * 128 + (g & 3) * 16) * D + col0;
; #pragma unroll
;                 for (int k = 0; k < 4; ++k) rin[gg][k] = *(const u32x2v*)(in + offn + (k >> 1) * 128 + (k & 1) * 16); }
; #pragma unroll
;             for (int gg = 0; gg < 4; ++gg) {
;                 const int g = hb * 4 + gg, ai = g >> 2, m = g & 3, row = row0 + ai * 128 + m * 16;
;                 const size_t off = (size_t)row * D + col0;
;                 float ss = 0.f;
; #pragma unroll
;                 for (int k = 0; k < 4; ++k) { const int bj = k >> 1, n = k & 1; const size_t o = off + bj * 128 + n * 16; const f32x4 a = acc[ai][bj][m][n] * scale; const u32x2v w0 = rin[gg][k];
;                     f32x4 r; r[0] = bflo(w0.x) + a[0]; r[1] = bfhi(w0.x) + a[1]; r[2] = bflo(w0.y) + a[2]; r[3] = bfhi(w0.y) + a[3];
;                     u32x2v w; w.x = pk2(r[0], r[1]); w.y = pk2(r[2], r[3]); *(u32x2v*)(out + o) = w; ss += (r[0] * r[0] + r[1] * r[1]) + (r[2] * r[2] + r[3] * r[3]); }
;                 ss += __shfl_xor(ss, 16); ss += __shfl_xor(ss, 32);
;                 if (fq == 0) part[(ai * 128 + wr * 64 + m * 16 + fr) * 4 + wc] = ss;
.LBB0_1271:
	s_mov_b64 s[100:101], 0x40000
	s_lshl_b32 s13, s13, 8
	v_lshl_or_b32 v136, s12, 8, v170
	v_readlane_b32 s80, v251, 12
	v_add_u32_e32 v138, s13, v168
	v_ashrrev_i32_e32 v137, 31, v136
	s_mov_b64 s[56:57], s[46:47]
	s_mov_b64 s[70:71], s[46:47]
	s_mov_b32 s90, 0.5
	v_readlane_b32 s81, v251, 13
	v_lshlrev_b64 v[140:141], 1, v[136:137]
	v_ashrrev_i32_e32 v139, 31, v138
	v_lshlrev_b64 v[142:143], 11, v[138:139]
	v_lshl_add_u64 v[136:137], s[56:57], 0, v[140:141]
	v_lshl_add_u64 v[144:145], v[136:137], 0, v[142:143]
	global_load_dwordx2 v[174:175], v[144:145], off
	global_load_dwordx2 v[176:177], v[144:145], off offset:32
	global_load_dwordx2 v[178:179], v[144:145], off offset:256
	global_load_dwordx2 v[180:181], v[144:145], off offset:288
	v_lshl_add_u64 v[202:203], v[144:145], 0, s[100:101]
	global_load_dwordx2 v[204:205], v[202:203], off
	global_load_dwordx2 v[206:207], v[202:203], off offset:32
	global_load_dwordx2 v[210:211], v[202:203], off offset:256
	global_load_dwordx2 v[212:213], v[202:203], off offset:288
	v_or_b32_e32 v144, 16, v138
	v_or_b32_e32 v146, 32, v138
	v_or_b32_e32 v150, 48, v138
	v_ashrrev_i32_e32 v145, 31, v144
	v_ashrrev_i32_e32 v147, 31, v146
	v_ashrrev_i32_e32 v151, 31, v150
	v_lshlrev_b64 v[166:167], 11, v[144:145]
	v_lshlrev_b64 v[148:149], 11, v[146:147]
	v_pk_mul_f32 v[182:183], v[128:129], s[90:91] op_sel_hi:[1,0]
	v_pk_mul_f32 v[188:189], v[122:123], s[90:91] op_sel_hi:[1,0]
	v_pk_mul_f32 v[190:191], v[120:121], s[90:91] op_sel_hi:[1,0]
	v_pk_mul_f32 v[192:193], v[118:119], s[90:91] op_sel_hi:[1,0]
	v_lshl_add_u64 v[118:119], s[70:71], 0, v[140:141]
	v_lshlrev_b64 v[128:129], 11, v[150:151]
	v_lshl_add_u64 v[120:121], v[136:137], 0, v[166:167]
	v_lshl_add_u64 v[122:123], v[136:137], 0, v[148:149]
	v_pk_mul_f32 v[184:185], v[126:127], s[90:91] op_sel_hi:[1,0]
	v_pk_mul_f32 v[186:187], v[124:125], s[90:91] op_sel_hi:[1,0]
	v_lshl_add_u64 v[194:195], v[118:119], 0, v[142:143]
	v_lshl_add_u64 v[196:197], v[136:137], 0, v[128:129]
	global_load_dwordx2 v[156:157], v[120:121], off
	global_load_dwordx2 v[154:155], v[120:121], off offset:32
	global_load_dwordx2 v[152:153], v[120:121], off offset:256
	global_load_dwordx2 v[150:151], v[120:121], off offset:288
	v_lshl_add_u64 v[202:203], v[120:121], 0, s[100:101]
	global_load_dwordx2 v[214:215], v[202:203], off
	global_load_dwordx2 v[216:217], v[202:203], off offset:32
	global_load_dwordx2 v[218:219], v[202:203], off offset:256
	global_load_dwordx2 v[220:221], v[202:203], off offset:288
	global_load_dwordx2 v[146:147], v[122:123], off
	global_load_dwordx2 v[144:145], v[122:123], off offset:32
	global_load_dwordx2 v[142:143], v[122:123], off offset:256
	global_load_dwordx2 v[140:141], v[122:123], off offset:288
	v_lshl_add_u64 v[202:203], v[122:123], 0, s[100:101]
	global_load_dwordx2 v[222:223], v[202:203], off
	global_load_dwordx2 v[238:239], v[202:203], off offset:32
	global_load_dwordx2 v[240:241], v[202:203], off offset:256
	global_load_dwordx2 v[242:243], v[202:203], off offset:288
	global_load_dwordx2 v[126:127], v[196:197], off
	global_load_dwordx2 v[124:125], v[196:197], off offset:32
	s_nop 0
	global_load_dwordx2 v[122:123], v[196:197], off offset:256
	global_load_dwordx2 v[120:121], v[196:197], off offset:288
	v_lshl_add_u64 v[202:203], v[196:197], 0, s[100:101]
	global_load_dwordx2 v[244:245], v[202:203], off
	global_load_dwordx2 v[246:247], v[202:203], off offset:32
	global_load_dwordx2 v[252:253], v[202:203], off offset:256
	global_load_dwordx2 v[254:255], v[202:203], off offset:288
	v_pk_mul_f32 v[114:115], v[114:115], s[90:91] op_sel_hi:[1,0]
	v_pk_mul_f32 v[116:117], v[116:117], s[90:91] op_sel_hi:[1,0]
	s_waitcnt vmcnt(0) lgkmcnt(0)
	v_lshlrev_b32_e32 v173, 16, v174
	v_and_b32_e32 v174, 0xffff0000, v174
	v_lshlrev_b32_e32 v196, 16, v175
	v_and_b32_e32 v175, 0xffff0000, v175
	v_lshlrev_b32_e32 v197, 16, v176
	v_and_b32_e32 v176, 0xffff0000, v176
	v_lshlrev_b32_e32 v198, 16, v177
	v_and_b32_e32 v177, 0xffff0000, v177
	v_lshlrev_b32_e32 v200, 16, v179
	v_add_f32_e32 v173, v184, v173
	v_add_f32_e32 v184, v185, v174
	v_add_f32_e32 v183, v183, v175
	v_add_f32_e32 v176, v189, v176
	v_add_f32_e32 v177, v187, v177
	v_add_f32_e32 v182, v182, v196
	v_add_f32_e32 v185, v188, v197
	v_add_f32_e32 v186, v186, v198
	v_add_f32_e32 v188, v190, v200
	v_cvt_pk_bf16_f32 v174, v173, v184
	v_cvt_pk_bf16_f32 v175, v182, v183
	v_mul_f32_e32 v184, v184, v184
	v_mul_f32_e32 v183, v183, v183
	v_mul_f32_e32 v189, v176, v176
	v_mul_f32_e32 v190, v177, v177
	v_lshlrev_b32_e32 v199, 16, v178
	v_and_b32_e32 v178, 0xffff0000, v178
	v_and_b32_e32 v179, 0xffff0000, v179
	v_fmac_f32_e32 v184, v173, v173
	v_fmac_f32_e32 v183, v182, v182
	v_fmac_f32_e32 v189, v185, v185
	v_fmac_f32_e32 v190, v186, v186
	v_add_f32_e32 v178, v193, v178
	v_add_f32_e32 v179, v191, v179
	global_store_dwordx2 v[194:195], v[174:175], off
	v_add_f32_e32 v173, v184, v183
	v_add_f32_e32 v175, v189, v190
	v_add_f32_e32 v187, v192, v199
	v_mul_f32_e32 v191, v178, v178
	v_add_f32_e32 v173, v173, v175
	v_mul_f32_e32 v175, v179, v179
	v_fmac_f32_e32 v191, v187, v187
	v_fmac_f32_e32 v175, v188, v188
	v_add_f32_e32 v175, v191, v175
	v_add_f32_e32 v173, v173, v175
	v_lshlrev_b32_e32 v175, 16, v180
	v_cvt_pk_bf16_f32 v174, v185, v176
	v_add_f32_e32 v176, v114, v175
	v_and_b32_e32 v114, 0xffff0000, v180
	v_add_f32_e32 v180, v115, v114
	v_lshlrev_b32_e32 v114, 16, v181
	v_add_f32_e32 v182, v116, v114
	v_and_b32_e32 v114, 0xffff0000, v181
	v_add_f32_e32 v181, v117, v114
	v_mul_f32_e32 v114, v180, v180
	v_mul_f32_e32 v115, v181, v181
	v_fmac_f32_e32 v114, v176, v176
	v_fmac_f32_e32 v115, v182, v182
	v_add_f32_e32 v114, v114, v115
	v_and_b32_e32 v116, 64, v209
	v_add_f32_e32 v115, v173, v114
	v_xor_b32_e32 v114, 16, v209
	v_add_u32_e32 v117, 64, v116
	v_cmp_lt_i32_e32 vcc, v114, v117
	v_cvt_pk_bf16_f32 v175, v186, v177
	global_store_dwordx2 v[194:195], v[174:175], off offset:32
	v_cvt_pk_bf16_f32 v174, v187, v178
	v_cvt_pk_bf16_f32 v175, v188, v179
	global_store_dwordx2 v[194:195], v[174:175], off offset:256
	v_cndmask_b32_e32 v114, v209, v114, vcc
	v_lshlrev_b32_e32 v114, 2, v114
	ds_bpermute_b32 v116, v114, v115
	v_cvt_pk_bf16_f32 v174, v176, v180
	v_cvt_pk_bf16_f32 v175, v182, v181
	global_store_dwordx2 v[194:195], v[174:175], off offset:288
	s_waitcnt lgkmcnt(0)
	v_add_f32_e32 v116, v115, v116
	v_xor_b32_e32 v115, 32, v209
	v_cmp_lt_i32_e32 vcc, v115, v117
	s_nop 1
	v_cndmask_b32_e32 v115, v209, v115, vcc
	v_lshlrev_b32_e32 v115, 2, v115
	ds_bpermute_b32 v117, v115, v116
	s_and_saveexec_b64 s[70:71], s[40:41]
	s_cbranch_execz .LBB0_1273
	s_waitcnt lgkmcnt(0)
	v_add_f32_e32 v116, v116, v117
	ds_write_b32 v171, v116

; __device__ __forceinline__ float bflo(unsigned w) { return __uint_as_float(w << 16); }
; __device__ __forceinline__ float bfhi(unsigned w) { return __uint_as_float(w & 0xffff0000u); }
; __device__ __forceinline__ unsigned pk2(float lo, float hi) { return pg8::cvt_pk_bf16(lo, hi); }
;     __device__ __forceinline__ void operator()(const f32x4 (&acc)[2][2][4][2], const Unit& u, int wr, int wc, int fr, int fq) const {
;     ...
;             for (int gg = 0; gg < 4; ++gg) { const int g = hb * 4 + gg; const size_t offn = (size_t)(row0 + (g >> 2) * 128 + (g & 3) * 16) * D + col0;
; #pragma unroll
;                 for (int k = 0; k < 4; ++k) rin[gg][k] = *(const u32x2v*)(in + offn + (k >> 1) * 128 + (k & 1) * 16); }
; #pragma unroll
;             for (int gg = 0; gg < 4; ++gg) {
;                 const int g = hb * 4 + gg, ai = g >> 2, m = g & 3, row = row0 + ai * 128 + m * 16;
;                 const size_t off = (size_t)row * D + col0;
;                 float ss = 0.f;
; #pragma unroll
;                 for (int k = 0; k < 4; ++k) { const int bj = k >> 1, n = k & 1; const size_t o = off + bj * 128 + n * 16; const f32x4 a = acc[ai][bj][m][n] * scale; const u32x2v w0 = rin[gg][k];
;                     f32x4 r; r[0] = bflo(w0.x) + a[0]; r[1] = bfhi(w0.x) + a[1]; r[2] = bflo(w0.y) + a[2]; r[3] = bfhi(w0.y) + a[3];
;                     u32x2v w; w.x = pk2(r[0], r[1]); w.y = pk2(r[2], r[3]); *(u32x2v*)(out + o) = w; ss += (r[0] * r[0] + r[1] * r[1]) + (r[2] * r[2] + r[3] * r[3]); }
;                 ss += __shfl_xor(ss, 16); ss += __shfl_xor(ss, 32);
;                 if (fq == 0) part[(ai * 128 + wr * 64 + m * 16 + fr) * 4 + wc] = ss;
.LBB0_1279:
	s_or_b64 exec, exec, s[92:93]
	s_waitcnt lgkmcnt(0)
	v_lshlrev_b64 v[66:67], 11, v[138:139]
	v_lshl_add_u64 v[98:99], v[66:67], 0, s[88:89]
	v_lshl_add_u64 v[68:69], v[136:137], 0, v[98:99]
	s_mov_b64 s[56:57], 0x48000
	v_lshl_add_u64 v[94:95], v[66:67], 0, s[56:57]
	s_mov_b64 s[56:57], 0x50000
	v_lshl_add_u64 v[84:85], v[66:67], 0, s[56:57]
	s_mov_b64 s[56:57], 0x58000
	v_lshl_add_u64 v[68:69], v[136:137], 0, v[94:95]
	v_lshl_add_u64 v[70:71], v[66:67], 0, s[56:57]
	v_lshl_add_u64 v[68:69], v[136:137], 0, v[84:85]
	v_lshl_add_u64 v[66:67], v[136:137], 0, v[70:71]
	s_nop 0
	s_nop 0
	v_pk_mul_f32 v[62:63], v[62:63], s[90:91]
	v_pk_mul_f32 v[64:65], v[64:65], s[70:71]
	v_lshl_add_u64 v[98:99], v[118:119], 0, v[98:99]
	v_pk_mul_f32 v[58:59], v[58:59], s[90:91]
	v_pk_mul_f32 v[60:61], v[60:61], s[70:71]
	v_pk_mul_f32 v[54:55], v[54:55], s[90:91]
	v_pk_mul_f32 v[56:57], v[56:57], s[70:71]
	v_pk_mul_f32 v[50:51], v[50:51], s[90:91]
	v_pk_mul_f32 v[52:53], v[52:53], s[70:71]
	s_waitcnt vmcnt(0) lgkmcnt(0)
	v_mov_b32_e32 v102, v204
	v_mov_b32_e32 v103, v205
	v_mov_b32_e32 v104, v206
	v_mov_b32_e32 v105, v207
	v_mov_b32_e32 v100, v210
	v_mov_b32_e32 v101, v211
	v_mov_b32_e32 v96, v212
	v_mov_b32_e32 v97, v213
	v_mov_b32_e32 v92, v214
	v_mov_b32_e32 v93, v215
	v_mov_b32_e32 v90, v216
	v_mov_b32_e32 v91, v217
	v_mov_b32_e32 v88, v218
	v_mov_b32_e32 v89, v219
	v_mov_b32_e32 v86, v220
	v_mov_b32_e32 v87, v221
	v_mov_b32_e32 v82, v222
	v_mov_b32_e32 v83, v223
	v_mov_b32_e32 v80, v238
	v_mov_b32_e32 v81, v239
	v_mov_b32_e32 v78, v240
	v_mov_b32_e32 v79, v241
	v_mov_b32_e32 v74, v242
	v_mov_b32_e32 v75, v243
	v_mov_b32_e32 v76, v244
	v_mov_b32_e32 v77, v245
	v_mov_b32_e32 v72, v246
	v_mov_b32_e32 v73, v247
	v_mov_b32_e32 v68, v252
	v_mov_b32_e32 v69, v253
	v_mov_b32_e32 v66, v254
	v_mov_b32_e32 v67, v255
	v_lshlrev_b32_e32 v106, 16, v102
	v_add_f32_e32 v106, v62, v106
	v_and_b32_e32 v62, 0xffff0000, v102
	v_add_f32_e32 v102, v63, v62
	v_lshlrev_b32_e32 v62, 16, v103
	v_add_f32_e32 v64, v64, v62
	v_and_b32_e32 v62, 0xffff0000, v103
	v_add_f32_e32 v65, v65, v62
	v_cvt_pk_bf16_f32 v62, v106, v102
	v_cvt_pk_bf16_f32 v63, v64, v65
	global_store_dwordx2 v[98:99], v[62:63], off
	v_mul_f32_e32 v62, v102, v102
	v_mul_f32_e32 v63, v65, v65
	v_fmac_f32_e32 v62, v106, v106
	v_fmac_f32_e32 v63, v64, v64
	v_add_f32_e32 v62, v62, v63
	v_lshlrev_b32_e32 v63, 16, v104
	v_add_f32_e32 v63, v58, v63
	v_and_b32_e32 v58, 0xffff0000, v104
	v_add_f32_e32 v64, v59, v58
	v_lshlrev_b32_e32 v58, 16, v105
	v_add_f32_e32 v60, v60, v58
	v_and_b32_e32 v58, 0xffff0000, v105
	v_add_f32_e32 v61, v61, v58
	v_cvt_pk_bf16_f32 v58, v63, v64
	v_cvt_pk_bf16_f32 v59, v60, v61
	global_store_dwordx2 v[98:99], v[58:59], off offset:32
	v_mul_f32_e32 v58, v64, v64
	v_mul_f32_e32 v59, v61, v61
	v_fmac_f32_e32 v58, v63, v63
	v_fmac_f32_e32 v59, v60, v60
	v_add_f32_e32 v58, v58, v59
	v_lshlrev_b32_e32 v59, 16, v100
	v_add_f32_e32 v59, v54, v59
	v_and_b32_e32 v54, 0xffff0000, v100
	v_add_f32_e32 v60, v55, v54
	v_lshlrev_b32_e32 v54, 16, v101
	v_add_f32_e32 v56, v56, v54
	v_and_b32_e32 v54, 0xffff0000, v101
	v_add_f32_e32 v57, v57, v54
	v_cvt_pk_bf16_f32 v54, v59, v60
	v_cvt_pk_bf16_f32 v55, v56, v57
	global_store_dwordx2 v[98:99], v[54:55], off offset:256
	v_mul_f32_e32 v54, v60, v60
	v_mul_f32_e32 v55, v57, v57
	v_fmac_f32_e32 v54, v59, v59
	v_fmac_f32_e32 v55, v56, v56
	v_add_f32_e32 v54, v54, v55
	v_lshlrev_b32_e32 v55, 16, v96
	v_add_f32_e32 v55, v50, v55
	v_and_b32_e32 v50, 0xffff0000, v96
	v_add_f32_e32 v56, v51, v50
	v_lshlrev_b32_e32 v50, 16, v97
	v_add_f32_e32 v52, v52, v50
	v_and_b32_e32 v50, 0xffff0000, v97
	v_add_f32_e32 v53, v53, v50
	v_cvt_pk_bf16_f32 v50, v55, v56
	v_cvt_pk_bf16_f32 v51, v52, v53
	global_store_dwordx2 v[98:99], v[50:51], off offset:288
	v_mul_f32_e32 v50, v56, v56
	v_mul_f32_e32 v51, v53, v53
	v_add_f32_e32 v58, v62, v58
	v_fmac_f32_e32 v50, v55, v55
	v_fmac_f32_e32 v51, v52, v52
	v_add_f32_e32 v54, v58, v54
	v_add_f32_e32 v50, v50, v51
	v_add_f32_e32 v50, v54, v50
	ds_bpermute_b32 v51, v114, v50
	s_waitcnt lgkmcnt(0)
	v_add_f32_e32 v50, v50, v51
	ds_bpermute_b32 v51, v115, v50
	s_and_saveexec_b64 s[70:71], s[40:41]
	s_cbranch_execz .LBB0_1281
	s_waitcnt lgkmcnt(0)
	v_add_f32_e32 v50, v50, v51
	ds_write_b32 v171, v50 offset:2048
